# short gated conv rewritten by hand: one token row per wave, the eight 16-byte loads of a row issued together, next row in flight under the arithmetic; conv taps loaded once
# speedup vs baseline: 1.0634x; 1.0042x over previous
; DI float bflo(unsigned w) { return __uint_as_float(w << 16); }
; DI float bfhi(unsigned w) { return __uint_as_float(w & 0xffff0000u); }
; DI int ltid() { int t; asm volatile("v_mov_b32 %0, %1" : "=v"(t) : "v"(threadIdx.x)); return t; }
; DI float silu(float z) { return z / (1.f + __expf(-z)); }
; DI void phase_mix_even(char* lds, const Params& p, int layer, int dry) {
;     ...
;   const float* cw = p.conv_w + e * 3 * 512;
;   for (int idx = blockIdx.x * NTHREADS + ltid(); idx < NTOK * 64; idx += gridDim.x * NTHREADS) {
;     const int t = idx >> 6, c0 = (idx & 63) * 8;
;     int S, seq0, pos, sq; tok_info(t, S, seq0, pos, sq);
;     bf16_t* ur = p.u + (size_t)t * UW;
;     float ic[8], il[8], ir[8];
;     { const u32x4 a = *(const u32x4*)(ur + 512 + c0), b = *(const u32x4*)(ur + 1024 + c0);
; #pragma unroll
;       for (int j = 0; j < 4; ++j) { ic[2 * j] = bflo(a[j]) * bflo(b[j]); ic[2 * j + 1] = bfhi(a[j]) * bfhi(b[j]); } }
;     if (pos > 0) { const u32x4 a = *(const u32x4*)(ur - UW + 512 + c0), b = *(const u32x4*)(ur - UW + 1024 + c0);
; #pragma unroll
;       for (int j = 0; j < 4; ++j) { il[2 * j] = bflo(a[j]) * bflo(b[j]); il[2 * j + 1] = bfhi(a[j]) * bfhi(b[j]); } }
;     else {
; #pragma unroll
;       for (int j = 0; j < 8; ++j) il[j] = 0.f; }
;     if (pos < S - 1) { const u32x4 a = *(const u32x4*)(ur + UW + 512 + c0), b = *(const u32x4*)(ur + UW + 1024 + c0);
; #pragma unroll
;       for (int j = 0; j < 4; ++j) { ir[2 * j] = bflo(a[j]) * bflo(b[j]); ir[2 * j + 1] = bfhi(a[j]) * bfhi(b[j]); } }
;     else {
; #pragma unroll
;       for (int j = 0; j < 8; ++j) ir[j] = 0.f; }
;     const u32x4 gbw = *(const u32x4*)(ur + c0), zw = *(const u32x4*)(ur + 2560 + c0);
;     float y[8];
; #pragma unroll
;     for (int j = 0; j < 8; ++j) {
;       const float gb = (j & 1) ? bfhi(gbw[j >> 1]) : bflo(gbw[j >> 1]);
;       const float z = (j & 1) ? bfhi(zw[j >> 1]) : bflo(zw[j >> 1]);
;       const float cv = il[j] * cw[c0 + j] + ic[j] * cw[512 + c0 + j] + ir[j] * cw[1024 + c0 + j];
;       y[j] = gb * cv * silu(z);
.LBB0_451:
	s_mov_b64 s[0:1], exec
	s_and_b64 vcc, exec, s[24:25]
	s_cbranch_vccz .LBB0_215
	v_and_b32_e32 v0, 63, v212
	v_lshlrev_b32_e32 v2, 4, v0
	v_add_u32_e32 v25, 0x1000, v2
	v_lshlrev_b32_e32 v3, 5, v0
	v_add_u32_e32 v24, 0x1000, v3
	global_load_dwordx4 v[4:7], v3, s[16:17]
	global_load_dwordx4 v[8:11], v3, s[16:17] offset:16
	global_load_dwordx4 v[12:15], v3, s[16:17] offset:2048
	global_load_dwordx4 v[16:19], v3, s[16:17] offset:2064
	global_load_dwordx4 v[20:23], v24, s[16:17]
	global_load_dwordx4 v[26:29], v24, s[16:17] offset:16
	v_readlane_b32 s48, v254, 37
	v_readlane_b32 s49, v254, 38
	v_readfirstlane_b32 s1, v212
	s_lshr_b32 s1, s1, 6
	v_readlane_b32 s0, v254, 0
	s_lshl_b32 s0, s0, 3
	s_add_i32 s0, s0, s1
	s_lshl_b32 s50, s28, 3
	s_mov_b32 s54, s0
	s_min_u32 s51, s0, 0x17fff
	s_cmp_lt_u32 s51, 0x10000
	s_movk_i32 s1, 0xfff
	s_cselect_b32 s1, 0x1fff, s1
	s_and_b32 s5, s51, s1
	s_mul_i32 s2, s51, 0x1e00
	s_add_u32 s2, s2, s48
	s_addc_u32 s3, s49, 0
	s_cmp_lg_u32 s5, 0
	s_cselect_b64 s[40:41], -1, 0
	s_cselect_b32 s4, 0x1e00, 0
	s_cmp_lg_u32 s5, s1
	s_cselect_b64 s[42:43], -1, 0
	s_cselect_b32 s8, 0x1e00, 0
	s_sub_u32 s4, s2, s4
	s_subb_u32 s5, s3, 0
	s_add_u32 s8, s2, s8
	s_addc_u32 s9, s3, 0
	global_load_dwordx4 v[32:35], v2, s[2:3] offset:1024
	global_load_dwordx4 v[36:39], v2, s[2:3] offset:2048
	global_load_dwordx4 v[40:43], v2, s[2:3]
	global_load_dwordx4 v[44:47], v25, s[2:3] offset:1024
	global_load_dwordx4 v[48:51], v2, s[4:5] offset:1024
	global_load_dwordx4 v[52:55], v2, s[4:5] offset:2048
	global_load_dwordx4 v[56:59], v2, s[8:9] offset:1024
	global_load_dwordx4 v[60:63], v2, s[8:9] offset:2048
	s_add_i32 s0, s0, s50
	s_mov_b32 s55, s0
	s_min_u32 s51, s0, 0x17fff
	s_cmp_lt_u32 s51, 0x10000
	s_movk_i32 s1, 0xfff
	s_cselect_b32 s1, 0x1fff, s1
	s_and_b32 s5, s51, s1
	s_mul_i32 s10, s51, 0x1e00
	s_add_u32 s10, s10, s48
	s_addc_u32 s11, s49, 0
	s_cmp_lg_u32 s5, 0
	s_cselect_b64 s[44:45], -1, 0
	s_cselect_b32 s4, 0x1e00, 0
	s_cmp_lg_u32 s5, s1
	s_cselect_b64 s[46:47], -1, 0
	s_cselect_b32 s8, 0x1e00, 0
	s_sub_u32 s4, s10, s4
	s_subb_u32 s5, s11, 0
	s_add_u32 s8, s10, s8
	s_addc_u32 s9, s11, 0
	global_load_dwordx4 v[64:67], v2, s[10:11] offset:1024
	global_load_dwordx4 v[68:71], v2, s[10:11] offset:2048
	global_load_dwordx4 v[72:75], v2, s[10:11]
	global_load_dwordx4 v[76:79], v25, s[10:11] offset:1024
	global_load_dwordx4 v[80:83], v2, s[4:5] offset:1024
	global_load_dwordx4 v[84:87], v2, s[4:5] offset:2048
	global_load_dwordx4 v[88:91], v2, s[8:9] offset:1024
	global_load_dwordx4 v[92:95], v2, s[8:9] offset:2048
	s_add_i32 s0, s0, s50
.Lcv_loop:
	s_waitcnt vmcnt(8)
	v_cndmask_b32_e64 v48, 0, v48, s[40:41]
	v_cndmask_b32_e64 v56, 0, v56, s[42:43]
	v_cndmask_b32_e64 v49, 0, v49, s[40:41]
	v_cndmask_b32_e64 v57, 0, v57, s[42:43]
	v_cndmask_b32_e64 v50, 0, v50, s[40:41]
	v_cndmask_b32_e64 v58, 0, v58, s[42:43]
	v_cndmask_b32_e64 v51, 0, v51, s[40:41]
	v_cndmask_b32_e64 v59, 0, v59, s[42:43]
	v_lshlrev_b32_e32 v96, 16, v32
	v_and_b32_e32 v97, 0xffff0000, v32
	v_lshlrev_b32_e32 v98, 16, v36
	v_and_b32_e32 v99, 0xffff0000, v36
	v_lshlrev_b32_e32 v100, 16, v48
	v_and_b32_e32 v101, 0xffff0000, v48
	v_lshlrev_b32_e32 v102, 16, v52
	v_and_b32_e32 v103, 0xffff0000, v52
	v_lshlrev_b32_e32 v104, 16, v56
	v_and_b32_e32 v105, 0xffff0000, v56
	v_lshlrev_b32_e32 v106, 16, v60
	v_and_b32_e32 v107, 0xffff0000, v60
	v_lshlrev_b32_e32 v108, 16, v40
	v_and_b32_e32 v109, 0xffff0000, v40
	v_lshlrev_b32_e32 v110, 16, v44
	v_and_b32_e32 v111, 0xffff0000, v44
	v_mul_f32_e32 v112, v96, v98
	v_mul_f32_e32 v113, v100, v102
	v_mul_f32_e32 v114, v104, v106
	v_mul_f32_e32 v115, v113, v4
	v_fmac_f32_e32 v115, v112, v12
	v_fmac_f32_e32 v115, v114, v20
	v_mul_f32_e32 v115, v108, v115
	v_mul_f32_e32 v116, 0xbfb8aa3b, v110
	v_exp_f32_e32 v116, v116
	s_nop 0
	v_add_f32_e32 v116, 1.0, v116
	v_div_scale_f32 v118, s[52:53], v116, v116, v110
	v_rcp_f32_e32 v119, v118
	s_nop 0
	v_fma_f32 v120, -v118, v119, 1.0
	v_fmac_f32_e32 v119, v120, v119
	v_div_scale_f32 v120, vcc, v110, v116, v110
	v_mul_f32_e32 v121, v120, v119
	v_fma_f32 v122, -v118, v121, v120
	v_fmac_f32_e32 v121, v122, v119
	v_fma_f32 v118, -v118, v121, v120
	v_div_fmas_f32 v118, v118, v119, v121
	v_div_fixup_f32 v117, v118, v116, v110
	v_mul_f32_e32 v124, v115, v117
	v_mul_f32_e32 v112, v97, v99
	v_mul_f32_e32 v113, v101, v103
	v_mul_f32_e32 v114, v105, v107
	v_mul_f32_e32 v115, v113, v5
	v_fmac_f32_e32 v115, v112, v13
	v_fmac_f32_e32 v115, v114, v21
	v_mul_f32_e32 v115, v109, v115
	v_mul_f32_e32 v116, 0xbfb8aa3b, v111
	v_exp_f32_e32 v116, v116
	s_nop 0
	v_add_f32_e32 v116, 1.0, v116
	v_div_scale_f32 v118, s[52:53], v116, v116, v111
	v_rcp_f32_e32 v119, v118
	s_nop 0
	v_fma_f32 v120, -v118, v119, 1.0
	v_fmac_f32_e32 v119, v120, v119
	v_div_scale_f32 v120, vcc, v111, v116, v111
	v_mul_f32_e32 v121, v120, v119
	v_fma_f32 v122, -v118, v121, v120
	v_fmac_f32_e32 v121, v122, v119
	v_fma_f32 v118, -v118, v121, v120
	v_div_fmas_f32 v118, v118, v119, v121
	v_div_fixup_f32 v117, v118, v116, v111
	v_mul_f32_e32 v125, v115, v117
	v_cvt_pk_bf16_f32 v128, v124, v125
	v_lshlrev_b32_e32 v96, 16, v33
	v_and_b32_e32 v97, 0xffff0000, v33
	v_lshlrev_b32_e32 v98, 16, v37
	v_and_b32_e32 v99, 0xffff0000, v37
	v_lshlrev_b32_e32 v100, 16, v49
	v_and_b32_e32 v101, 0xffff0000, v49
	v_lshlrev_b32_e32 v102, 16, v53
	v_and_b32_e32 v103, 0xffff0000, v53
	v_lshlrev_b32_e32 v104, 16, v57
	v_and_b32_e32 v105, 0xffff0000, v57
	v_lshlrev_b32_e32 v106, 16, v61
	v_and_b32_e32 v107, 0xffff0000, v61
	v_lshlrev_b32_e32 v108, 16, v41
	v_and_b32_e32 v109, 0xffff0000, v41
	v_lshlrev_b32_e32 v110, 16, v45
	v_and_b32_e32 v111, 0xffff0000, v45
; DI unsigned cvtpk(float lo, float hi) { f32x2 v = {lo, hi}; bf16x2_t b = __builtin_convertvector(v, bf16x2_t); return __builtin_bit_cast(unsigned, b); }
; DI float bflo(unsigned w) { return __uint_as_float(w << 16); }
; DI float bfhi(unsigned w) { return __uint_as_float(w & 0xffff0000u); }
; DI float silu(float z) { return z / (1.f + __expf(-z)); }
; DI void phase_mix_even(char* lds, const Params& p, int layer, int dry) {
;     ...
;     const u32x4 gbw = *(const u32x4*)(ur + c0), zw = *(const u32x4*)(ur + 2560 + c0);
;     float y[8];
; #pragma unroll
;     for (int j = 0; j < 8; ++j) {
;       const float gb = (j & 1) ? bfhi(gbw[j >> 1]) : bflo(gbw[j >> 1]);
;       const float z = (j & 1) ? bfhi(zw[j >> 1]) : bflo(zw[j >> 1]);
;       const float cv = il[j] * cw[c0 + j] + ic[j] * cw[512 + c0 + j] + ir[j] * cw[1024 + c0 + j];
;       y[j] = gb * cv * silu(z);
;     }
;     u32x4 w; w.x = cvtpk(y[0], y[1]); w.y = cvtpk(y[2], y[3]); w.z = cvtpk(y[4], y[5]); w.w = cvtpk(y[6], y[7]);
;     if (!dry) *(u32x4*)(ur + c0) = w;
	v_mul_f32_e32 v112, v96, v98
	v_mul_f32_e32 v113, v100, v102
	v_mul_f32_e32 v114, v104, v106
	v_mul_f32_e32 v115, v113, v6
	v_fmac_f32_e32 v115, v112, v14
	v_fmac_f32_e32 v115, v114, v22
	v_mul_f32_e32 v115, v108, v115
	v_mul_f32_e32 v116, 0xbfb8aa3b, v110
	v_exp_f32_e32 v116, v116
	s_nop 0
	v_add_f32_e32 v116, 1.0, v116
	v_div_scale_f32 v118, s[52:53], v116, v116, v110
	v_rcp_f32_e32 v119, v118
	s_nop 0
	v_fma_f32 v120, -v118, v119, 1.0
	v_fmac_f32_e32 v119, v120, v119
	v_div_scale_f32 v120, vcc, v110, v116, v110
	v_mul_f32_e32 v121, v120, v119
	v_fma_f32 v122, -v118, v121, v120
	v_fmac_f32_e32 v121, v122, v119
	v_fma_f32 v118, -v118, v121, v120
	v_div_fmas_f32 v118, v118, v119, v121
	v_div_fixup_f32 v117, v118, v116, v110
	v_mul_f32_e32 v124, v115, v117
	v_mul_f32_e32 v112, v97, v99
	v_mul_f32_e32 v113, v101, v103
	v_mul_f32_e32 v114, v105, v107
	v_mul_f32_e32 v115, v113, v7
	v_fmac_f32_e32 v115, v112, v15
	v_fmac_f32_e32 v115, v114, v23
	v_mul_f32_e32 v115, v109, v115
	v_mul_f32_e32 v116, 0xbfb8aa3b, v111
	v_exp_f32_e32 v116, v116
	s_nop 0
	v_add_f32_e32 v116, 1.0, v116
	v_div_scale_f32 v118, s[52:53], v116, v116, v111
	v_rcp_f32_e32 v119, v118
	s_nop 0
	v_fma_f32 v120, -v118, v119, 1.0
	v_fmac_f32_e32 v119, v120, v119
	v_div_scale_f32 v120, vcc, v111, v116, v111
	v_mul_f32_e32 v121, v120, v119
	v_fma_f32 v122, -v118, v121, v120
	v_fmac_f32_e32 v121, v122, v119
	v_fma_f32 v118, -v118, v121, v120
	v_div_fmas_f32 v118, v118, v119, v121
	v_div_fixup_f32 v117, v118, v116, v111
	v_mul_f32_e32 v125, v115, v117
	v_cvt_pk_bf16_f32 v129, v124, v125
	v_lshlrev_b32_e32 v96, 16, v34
	v_and_b32_e32 v97, 0xffff0000, v34
	v_lshlrev_b32_e32 v98, 16, v38
	v_and_b32_e32 v99, 0xffff0000, v38
	v_lshlrev_b32_e32 v100, 16, v50
	v_and_b32_e32 v101, 0xffff0000, v50
	v_lshlrev_b32_e32 v102, 16, v54
	v_and_b32_e32 v103, 0xffff0000, v54
	v_lshlrev_b32_e32 v104, 16, v58
	v_and_b32_e32 v105, 0xffff0000, v58
	v_lshlrev_b32_e32 v106, 16, v62
	v_and_b32_e32 v107, 0xffff0000, v62
	v_lshlrev_b32_e32 v108, 16, v42
	v_and_b32_e32 v109, 0xffff0000, v42
	v_lshlrev_b32_e32 v110, 16, v46
	v_and_b32_e32 v111, 0xffff0000, v46
	v_mul_f32_e32 v112, v96, v98
	v_mul_f32_e32 v113, v100, v102
	v_mul_f32_e32 v114, v104, v106
	v_mul_f32_e32 v115, v113, v8
	v_fmac_f32_e32 v115, v112, v16
	v_fmac_f32_e32 v115, v114, v26
	v_mul_f32_e32 v115, v108, v115
	v_mul_f32_e32 v116, 0xbfb8aa3b, v110
	v_exp_f32_e32 v116, v116
	s_nop 0
	v_add_f32_e32 v116, 1.0, v116
	v_div_scale_f32 v118, s[52:53], v116, v116, v110
	v_rcp_f32_e32 v119, v118
	s_nop 0
	v_fma_f32 v120, -v118, v119, 1.0
	v_fmac_f32_e32 v119, v120, v119
	v_div_scale_f32 v120, vcc, v110, v116, v110
	v_mul_f32_e32 v121, v120, v119
	v_fma_f32 v122, -v118, v121, v120
	v_fmac_f32_e32 v121, v122, v119
	v_fma_f32 v118, -v118, v121, v120
	v_div_fmas_f32 v118, v118, v119, v121
	v_div_fixup_f32 v117, v118, v116, v110
	v_mul_f32_e32 v124, v115, v117
	v_mul_f32_e32 v112, v97, v99
	v_mul_f32_e32 v113, v101, v103
	v_mul_f32_e32 v114, v105, v107
	v_mul_f32_e32 v115, v113, v9
	v_fmac_f32_e32 v115, v112, v17
	v_fmac_f32_e32 v115, v114, v27
	v_mul_f32_e32 v115, v109, v115
	v_mul_f32_e32 v116, 0xbfb8aa3b, v111
	v_exp_f32_e32 v116, v116
	s_nop 0
	v_add_f32_e32 v116, 1.0, v116
	v_div_scale_f32 v118, s[52:53], v116, v116, v111
	v_rcp_f32_e32 v119, v118
	s_nop 0
	v_fma_f32 v120, -v118, v119, 1.0
	v_fmac_f32_e32 v119, v120, v119
	v_div_scale_f32 v120, vcc, v111, v116, v111
	v_mul_f32_e32 v121, v120, v119
	v_fma_f32 v122, -v118, v121, v120
	v_fmac_f32_e32 v121, v122, v119
	v_fma_f32 v118, -v118, v121, v120
	v_div_fmas_f32 v118, v118, v119, v121
	v_div_fixup_f32 v117, v118, v116, v111
	v_mul_f32_e32 v125, v115, v117
	v_cvt_pk_bf16_f32 v130, v124, v125
	v_lshlrev_b32_e32 v96, 16, v35
	v_and_b32_e32 v97, 0xffff0000, v35
	v_lshlrev_b32_e32 v98, 16, v39
	v_and_b32_e32 v99, 0xffff0000, v39
	v_lshlrev_b32_e32 v100, 16, v51
	v_and_b32_e32 v101, 0xffff0000, v51
	v_lshlrev_b32_e32 v102, 16, v55
	v_and_b32_e32 v103, 0xffff0000, v55
	v_lshlrev_b32_e32 v104, 16, v59
	v_and_b32_e32 v105, 0xffff0000, v59
	v_lshlrev_b32_e32 v106, 16, v63
	v_and_b32_e32 v107, 0xffff0000, v63
	v_lshlrev_b32_e32 v108, 16, v43
	v_and_b32_e32 v109, 0xffff0000, v43
	v_lshlrev_b32_e32 v110, 16, v47
	v_and_b32_e32 v111, 0xffff0000, v47
	v_mul_f32_e32 v112, v96, v98
	v_mul_f32_e32 v113, v100, v102
	v_mul_f32_e32 v114, v104, v106
	v_mul_f32_e32 v115, v113, v10
	v_fmac_f32_e32 v115, v112, v18
	v_fmac_f32_e32 v115, v114, v28
	v_mul_f32_e32 v115, v108, v115
	v_mul_f32_e32 v116, 0xbfb8aa3b, v110
	v_exp_f32_e32 v116, v116
	s_nop 0
	v_add_f32_e32 v116, 1.0, v116
	v_div_scale_f32 v118, s[52:53], v116, v116, v110
	v_rcp_f32_e32 v119, v118
	s_nop 0
	v_fma_f32 v120, -v118, v119, 1.0
	v_fmac_f32_e32 v119, v120, v119
	v_div_scale_f32 v120, vcc, v110, v116, v110
	v_mul_f32_e32 v121, v120, v119
	v_fma_f32 v122, -v118, v121, v120
	v_fmac_f32_e32 v121, v122, v119
	v_fma_f32 v118, -v118, v121, v120
	v_div_fmas_f32 v118, v118, v119, v121
	v_div_fixup_f32 v117, v118, v116, v110
	v_mul_f32_e32 v124, v115, v117
	v_mul_f32_e32 v112, v97, v99
	v_mul_f32_e32 v113, v101, v103
	v_mul_f32_e32 v114, v105, v107
	v_mul_f32_e32 v115, v113, v11
	v_fmac_f32_e32 v115, v112, v19
	v_fmac_f32_e32 v115, v114, v29
	v_mul_f32_e32 v115, v109, v115
	v_mul_f32_e32 v116, 0xbfb8aa3b, v111
	v_exp_f32_e32 v116, v116
	s_nop 0
	v_add_f32_e32 v116, 1.0, v116
	v_div_scale_f32 v118, s[52:53], v116, v116, v111
	v_rcp_f32_e32 v119, v118
	s_nop 0
	v_fma_f32 v120, -v118, v119, 1.0
	v_fmac_f32_e32 v119, v120, v119
	v_div_scale_f32 v120, vcc, v111, v116, v111
	v_mul_f32_e32 v121, v120, v119
	v_fma_f32 v122, -v118, v121, v120
	v_fmac_f32_e32 v121, v122, v119
	v_fma_f32 v118, -v118, v121, v120
	v_div_fmas_f32 v118, v118, v119, v121
	v_div_fixup_f32 v117, v118, v116, v111
	v_mul_f32_e32 v125, v115, v117
	v_cvt_pk_bf16_f32 v131, v124, v125
	s_cmp_lt_u32 s54, 0x18000
	s_cbranch_scc0 .Lcv_nsA349
	global_store_dwordx4 v2, v[128:131], s[2:3]
; DI float bflo(unsigned w) { return __uint_as_float(w << 16); }
; DI float bfhi(unsigned w) { return __uint_as_float(w & 0xffff0000u); }
; DI int ltid() { int t; asm volatile("v_mov_b32 %0, %1" : "=v"(t) : "v"(threadIdx.x)); return t; }
; DI float silu(float z) { return z / (1.f + __expf(-z)); }
; DI void phase_mix_even(char* lds, const Params& p, int layer, int dry) {
;     ...
;   for (int idx = blockIdx.x * NTHREADS + ltid(); idx < NTOK * 64; idx += gridDim.x * NTHREADS) {
;     const int t = idx >> 6, c0 = (idx & 63) * 8;
;     int S, seq0, pos, sq; tok_info(t, S, seq0, pos, sq);
;     bf16_t* ur = p.u + (size_t)t * UW;
;     float ic[8], il[8], ir[8];
;     { const u32x4 a = *(const u32x4*)(ur + 512 + c0), b = *(const u32x4*)(ur + 1024 + c0);
; #pragma unroll
;       for (int j = 0; j < 4; ++j) { ic[2 * j] = bflo(a[j]) * bflo(b[j]); ic[2 * j + 1] = bfhi(a[j]) * bfhi(b[j]); } }
;     if (pos > 0) { const u32x4 a = *(const u32x4*)(ur - UW + 512 + c0), b = *(const u32x4*)(ur - UW + 1024 + c0);
; #pragma unroll
;       for (int j = 0; j < 4; ++j) { il[2 * j] = bflo(a[j]) * bflo(b[j]); il[2 * j + 1] = bfhi(a[j]) * bfhi(b[j]); } }
;     else {
; #pragma unroll
;       for (int j = 0; j < 8; ++j) il[j] = 0.f; }
;     if (pos < S - 1) { const u32x4 a = *(const u32x4*)(ur + UW + 512 + c0), b = *(const u32x4*)(ur + UW + 1024 + c0);
; #pragma unroll
;       for (int j = 0; j < 4; ++j) { ir[2 * j] = bflo(a[j]) * bflo(b[j]); ir[2 * j + 1] = bfhi(a[j]) * bfhi(b[j]); } }
;     else {
; #pragma unroll
;       for (int j = 0; j < 8; ++j) ir[j] = 0.f; }
;     const u32x4 gbw = *(const u32x4*)(ur + c0), zw = *(const u32x4*)(ur + 2560 + c0);
;     float y[8];
; #pragma unroll
;     for (int j = 0; j < 8; ++j) {
;       const float gb = (j & 1) ? bfhi(gbw[j >> 1]) : bflo(gbw[j >> 1]);
;       const float z = (j & 1) ? bfhi(zw[j >> 1]) : bflo(zw[j >> 1]);
;       const float cv = il[j] * cw[c0 + j] + ic[j] * cw[512 + c0 + j] + ir[j] * cw[1024 + c0 + j];
;       y[j] = gb * cv * silu(z);
.Lcv_nsA349:
	s_cmp_ge_u32 s55, 0x18000
	s_cbranch_scc1 .Lcv_done
	s_mov_b32 s54, s0
	s_min_u32 s51, s0, 0x17fff
	s_cmp_lt_u32 s51, 0x10000
	s_movk_i32 s1, 0xfff
	s_cselect_b32 s1, 0x1fff, s1
	s_and_b32 s5, s51, s1
	s_mul_i32 s2, s51, 0x1e00
	s_add_u32 s2, s2, s48
	s_addc_u32 s3, s49, 0
	s_cmp_lg_u32 s5, 0
	s_cselect_b64 s[40:41], -1, 0
	s_cselect_b32 s4, 0x1e00, 0
	s_cmp_lg_u32 s5, s1
	s_cselect_b64 s[42:43], -1, 0
	s_cselect_b32 s8, 0x1e00, 0
	s_sub_u32 s4, s2, s4
	s_subb_u32 s5, s3, 0
	s_add_u32 s8, s2, s8
	s_addc_u32 s9, s3, 0
	global_load_dwordx4 v[32:35], v2, s[2:3] offset:1024
	global_load_dwordx4 v[36:39], v2, s[2:3] offset:2048
	global_load_dwordx4 v[40:43], v2, s[2:3]
	global_load_dwordx4 v[44:47], v25, s[2:3] offset:1024
	global_load_dwordx4 v[48:51], v2, s[4:5] offset:1024
	global_load_dwordx4 v[52:55], v2, s[4:5] offset:2048
	global_load_dwordx4 v[56:59], v2, s[8:9] offset:1024
	global_load_dwordx4 v[60:63], v2, s[8:9] offset:2048
	s_add_i32 s0, s0, s50
	s_waitcnt vmcnt(9)
	v_cndmask_b32_e64 v80, 0, v80, s[44:45]
	v_cndmask_b32_e64 v88, 0, v88, s[46:47]
	v_cndmask_b32_e64 v81, 0, v81, s[44:45]
	v_cndmask_b32_e64 v89, 0, v89, s[46:47]
	v_cndmask_b32_e64 v82, 0, v82, s[44:45]
	v_cndmask_b32_e64 v90, 0, v90, s[46:47]
	v_cndmask_b32_e64 v83, 0, v83, s[44:45]
	v_cndmask_b32_e64 v91, 0, v91, s[46:47]
	v_lshlrev_b32_e32 v96, 16, v64
	v_and_b32_e32 v97, 0xffff0000, v64
	v_lshlrev_b32_e32 v98, 16, v68
	v_and_b32_e32 v99, 0xffff0000, v68
	v_lshlrev_b32_e32 v100, 16, v80
	v_and_b32_e32 v101, 0xffff0000, v80
	v_lshlrev_b32_e32 v102, 16, v84
	v_and_b32_e32 v103, 0xffff0000, v84
	v_lshlrev_b32_e32 v104, 16, v88
	v_and_b32_e32 v105, 0xffff0000, v88
	v_lshlrev_b32_e32 v106, 16, v92
	v_and_b32_e32 v107, 0xffff0000, v92
	v_lshlrev_b32_e32 v108, 16, v72
	v_and_b32_e32 v109, 0xffff0000, v72
	v_lshlrev_b32_e32 v110, 16, v76
	v_and_b32_e32 v111, 0xffff0000, v76
	v_mul_f32_e32 v112, v96, v98
	v_mul_f32_e32 v113, v100, v102
	v_mul_f32_e32 v114, v104, v106
	v_mul_f32_e32 v115, v113, v4
	v_fmac_f32_e32 v115, v112, v12
	v_fmac_f32_e32 v115, v114, v20
	v_mul_f32_e32 v115, v108, v115
	v_mul_f32_e32 v116, 0xbfb8aa3b, v110
	v_exp_f32_e32 v116, v116
	s_nop 0
	v_add_f32_e32 v116, 1.0, v116
	v_div_scale_f32 v118, s[52:53], v116, v116, v110
	v_rcp_f32_e32 v119, v118
	s_nop 0
	v_fma_f32 v120, -v118, v119, 1.0
	v_fmac_f32_e32 v119, v120, v119
	v_div_scale_f32 v120, vcc, v110, v116, v110
	v_mul_f32_e32 v121, v120, v119
	v_fma_f32 v122, -v118, v121, v120
	v_fmac_f32_e32 v121, v122, v119
	v_fma_f32 v118, -v118, v121, v120
	v_div_fmas_f32 v118, v118, v119, v121
	v_div_fixup_f32 v117, v118, v116, v110
	v_mul_f32_e32 v124, v115, v117
	v_mul_f32_e32 v112, v97, v99
	v_mul_f32_e32 v113, v101, v103
	v_mul_f32_e32 v114, v105, v107
	v_mul_f32_e32 v115, v113, v5
	v_fmac_f32_e32 v115, v112, v13
	v_fmac_f32_e32 v115, v114, v21
	v_mul_f32_e32 v115, v109, v115
	v_mul_f32_e32 v116, 0xbfb8aa3b, v111
	v_exp_f32_e32 v116, v116
	s_nop 0
	v_add_f32_e32 v116, 1.0, v116
	v_div_scale_f32 v118, s[52:53], v116, v116, v111
	v_rcp_f32_e32 v119, v118
	s_nop 0
	v_fma_f32 v120, -v118, v119, 1.0
	v_fmac_f32_e32 v119, v120, v119
	v_div_scale_f32 v120, vcc, v111, v116, v111
	v_mul_f32_e32 v121, v120, v119
	v_fma_f32 v122, -v118, v121, v120
	v_fmac_f32_e32 v121, v122, v119
	v_fma_f32 v118, -v118, v121, v120
	v_div_fmas_f32 v118, v118, v119, v121
	v_div_fixup_f32 v117, v118, v116, v111
	v_mul_f32_e32 v125, v115, v117
	v_cvt_pk_bf16_f32 v128, v124, v125
	v_lshlrev_b32_e32 v96, 16, v65
	v_and_b32_e32 v97, 0xffff0000, v65
	v_lshlrev_b32_e32 v98, 16, v69
	v_and_b32_e32 v99, 0xffff0000, v69
	v_lshlrev_b32_e32 v100, 16, v81
	v_and_b32_e32 v101, 0xffff0000, v81
	v_lshlrev_b32_e32 v102, 16, v85
	v_and_b32_e32 v103, 0xffff0000, v85
	v_lshlrev_b32_e32 v104, 16, v89
	v_and_b32_e32 v105, 0xffff0000, v89
	v_lshlrev_b32_e32 v106, 16, v93
	v_and_b32_e32 v107, 0xffff0000, v93
	v_lshlrev_b32_e32 v108, 16, v73
	v_and_b32_e32 v109, 0xffff0000, v73
	v_lshlrev_b32_e32 v110, 16, v77
	v_and_b32_e32 v111, 0xffff0000, v77
	v_mul_f32_e32 v112, v96, v98
	v_mul_f32_e32 v113, v100, v102
	v_mul_f32_e32 v114, v104, v106
	v_mul_f32_e32 v115, v113, v6
	v_fmac_f32_e32 v115, v112, v14
	v_fmac_f32_e32 v115, v114, v22
	v_mul_f32_e32 v115, v108, v115
	v_mul_f32_e32 v116, 0xbfb8aa3b, v110
	v_exp_f32_e32 v116, v116
	s_nop 0
	v_add_f32_e32 v116, 1.0, v116
	v_div_scale_f32 v118, s[52:53], v116, v116, v110
	v_rcp_f32_e32 v119, v118
	s_nop 0
	v_fma_f32 v120, -v118, v119, 1.0
	v_fmac_f32_e32 v119, v120, v119
	v_div_scale_f32 v120, vcc, v110, v116, v110
	v_mul_f32_e32 v121, v120, v119
	v_fma_f32 v122, -v118, v121, v120
	v_fmac_f32_e32 v121, v122, v119
	v_fma_f32 v118, -v118, v121, v120
	v_div_fmas_f32 v118, v118, v119, v121
	v_div_fixup_f32 v117, v118, v116, v110
	v_mul_f32_e32 v124, v115, v117
	v_mul_f32_e32 v112, v97, v99
	v_mul_f32_e32 v113, v101, v103
	v_mul_f32_e32 v114, v105, v107
	v_mul_f32_e32 v115, v113, v7
	v_fmac_f32_e32 v115, v112, v15
	v_fmac_f32_e32 v115, v114, v23
	v_mul_f32_e32 v115, v109, v115
	v_mul_f32_e32 v116, 0xbfb8aa3b, v111
	v_exp_f32_e32 v116, v116
	s_nop 0
	v_add_f32_e32 v116, 1.0, v116
	v_div_scale_f32 v118, s[52:53], v116, v116, v111
	v_rcp_f32_e32 v119, v118
	s_nop 0
	v_fma_f32 v120, -v118, v119, 1.0
	v_fmac_f32_e32 v119, v120, v119
	v_div_scale_f32 v120, vcc, v111, v116, v111
	v_mul_f32_e32 v121, v120, v119
	v_fma_f32 v122, -v118, v121, v120
	v_fmac_f32_e32 v121, v122, v119
	v_fma_f32 v118, -v118, v121, v120
	v_div_fmas_f32 v118, v118, v119, v121
	v_div_fixup_f32 v117, v118, v116, v111
	v_mul_f32_e32 v125, v115, v117
	v_cvt_pk_bf16_f32 v129, v124, v125
	v_lshlrev_b32_e32 v96, 16, v66
	v_and_b32_e32 v97, 0xffff0000, v66
; DI unsigned cvtpk(float lo, float hi) { f32x2 v = {lo, hi}; bf16x2_t b = __builtin_convertvector(v, bf16x2_t); return __builtin_bit_cast(unsigned, b); }
; DI float bflo(unsigned w) { return __uint_as_float(w << 16); }
; DI float bfhi(unsigned w) { return __uint_as_float(w & 0xffff0000u); }
; DI float silu(float z) { return z / (1.f + __expf(-z)); }
; DI void phase_mix_even(char* lds, const Params& p, int layer, int dry) {
;     ...
;     { const u32x4 a = *(const u32x4*)(ur + 512 + c0), b = *(const u32x4*)(ur + 1024 + c0);
; #pragma unroll
;       for (int j = 0; j < 4; ++j) { ic[2 * j] = bflo(a[j]) * bflo(b[j]); ic[2 * j + 1] = bfhi(a[j]) * bfhi(b[j]); } }
;     if (pos > 0) { const u32x4 a = *(const u32x4*)(ur - UW + 512 + c0), b = *(const u32x4*)(ur - UW + 1024 + c0);
; #pragma unroll
;       for (int j = 0; j < 4; ++j) { il[2 * j] = bflo(a[j]) * bflo(b[j]); il[2 * j + 1] = bfhi(a[j]) * bfhi(b[j]); } }
;     else {
; #pragma unroll
;       for (int j = 0; j < 8; ++j) il[j] = 0.f; }
;     if (pos < S - 1) { const u32x4 a = *(const u32x4*)(ur + UW + 512 + c0), b = *(const u32x4*)(ur + UW + 1024 + c0);
; #pragma unroll
;       for (int j = 0; j < 4; ++j) { ir[2 * j] = bflo(a[j]) * bflo(b[j]); ir[2 * j + 1] = bfhi(a[j]) * bfhi(b[j]); } }
;     else {
; #pragma unroll
;       for (int j = 0; j < 8; ++j) ir[j] = 0.f; }
;     const u32x4 gbw = *(const u32x4*)(ur + c0), zw = *(const u32x4*)(ur + 2560 + c0);
;     float y[8];
; #pragma unroll
;     for (int j = 0; j < 8; ++j) {
;       const float gb = (j & 1) ? bfhi(gbw[j >> 1]) : bflo(gbw[j >> 1]);
;       const float z = (j & 1) ? bfhi(zw[j >> 1]) : bflo(zw[j >> 1]);
;       const float cv = il[j] * cw[c0 + j] + ic[j] * cw[512 + c0 + j] + ir[j] * cw[1024 + c0 + j];
;       y[j] = gb * cv * silu(z);
;     }
;     u32x4 w; w.x = cvtpk(y[0], y[1]); w.y = cvtpk(y[2], y[3]); w.z = cvtpk(y[4], y[5]); w.w = cvtpk(y[6], y[7]);
;     if (!dry) *(u32x4*)(ur + c0) = w;
	v_lshlrev_b32_e32 v98, 16, v70
	v_and_b32_e32 v99, 0xffff0000, v70
	v_lshlrev_b32_e32 v100, 16, v82
	v_and_b32_e32 v101, 0xffff0000, v82
	v_lshlrev_b32_e32 v102, 16, v86
	v_and_b32_e32 v103, 0xffff0000, v86
	v_lshlrev_b32_e32 v104, 16, v90
	v_and_b32_e32 v105, 0xffff0000, v90
	v_lshlrev_b32_e32 v106, 16, v94
	v_and_b32_e32 v107, 0xffff0000, v94
	v_lshlrev_b32_e32 v108, 16, v74
	v_and_b32_e32 v109, 0xffff0000, v74
	v_lshlrev_b32_e32 v110, 16, v78
	v_and_b32_e32 v111, 0xffff0000, v78
	v_mul_f32_e32 v112, v96, v98
	v_mul_f32_e32 v113, v100, v102
	v_mul_f32_e32 v114, v104, v106
	v_mul_f32_e32 v115, v113, v8
	v_fmac_f32_e32 v115, v112, v16
	v_fmac_f32_e32 v115, v114, v26
	v_mul_f32_e32 v115, v108, v115
	v_mul_f32_e32 v116, 0xbfb8aa3b, v110
	v_exp_f32_e32 v116, v116
	s_nop 0
	v_add_f32_e32 v116, 1.0, v116
	v_div_scale_f32 v118, s[52:53], v116, v116, v110
	v_rcp_f32_e32 v119, v118
	s_nop 0
	v_fma_f32 v120, -v118, v119, 1.0
	v_fmac_f32_e32 v119, v120, v119
	v_div_scale_f32 v120, vcc, v110, v116, v110
	v_mul_f32_e32 v121, v120, v119
	v_fma_f32 v122, -v118, v121, v120
	v_fmac_f32_e32 v121, v122, v119
	v_fma_f32 v118, -v118, v121, v120
	v_div_fmas_f32 v118, v118, v119, v121
	v_div_fixup_f32 v117, v118, v116, v110
	v_mul_f32_e32 v124, v115, v117
	v_mul_f32_e32 v112, v97, v99
	v_mul_f32_e32 v113, v101, v103
	v_mul_f32_e32 v114, v105, v107
	v_mul_f32_e32 v115, v113, v9
	v_fmac_f32_e32 v115, v112, v17
	v_fmac_f32_e32 v115, v114, v27
	v_mul_f32_e32 v115, v109, v115
	v_mul_f32_e32 v116, 0xbfb8aa3b, v111
	v_exp_f32_e32 v116, v116
	s_nop 0
	v_add_f32_e32 v116, 1.0, v116
	v_div_scale_f32 v118, s[52:53], v116, v116, v111
	v_rcp_f32_e32 v119, v118
	s_nop 0
	v_fma_f32 v120, -v118, v119, 1.0
	v_fmac_f32_e32 v119, v120, v119
	v_div_scale_f32 v120, vcc, v111, v116, v111
	v_mul_f32_e32 v121, v120, v119
	v_fma_f32 v122, -v118, v121, v120
	v_fmac_f32_e32 v121, v122, v119
	v_fma_f32 v118, -v118, v121, v120
	v_div_fmas_f32 v118, v118, v119, v121
	v_div_fixup_f32 v117, v118, v116, v111
	v_mul_f32_e32 v125, v115, v117
	v_cvt_pk_bf16_f32 v130, v124, v125
	v_lshlrev_b32_e32 v96, 16, v67
	v_and_b32_e32 v97, 0xffff0000, v67
	v_lshlrev_b32_e32 v98, 16, v71
	v_and_b32_e32 v99, 0xffff0000, v71
	v_lshlrev_b32_e32 v100, 16, v83
	v_and_b32_e32 v101, 0xffff0000, v83
	v_lshlrev_b32_e32 v102, 16, v87
	v_and_b32_e32 v103, 0xffff0000, v87
	v_lshlrev_b32_e32 v104, 16, v91
	v_and_b32_e32 v105, 0xffff0000, v91
	v_lshlrev_b32_e32 v106, 16, v95
	v_and_b32_e32 v107, 0xffff0000, v95
	v_lshlrev_b32_e32 v108, 16, v75
	v_and_b32_e32 v109, 0xffff0000, v75
	v_lshlrev_b32_e32 v110, 16, v79
	v_and_b32_e32 v111, 0xffff0000, v79
	v_mul_f32_e32 v112, v96, v98
	v_mul_f32_e32 v113, v100, v102
	v_mul_f32_e32 v114, v104, v106
	v_mul_f32_e32 v115, v113, v10
	v_fmac_f32_e32 v115, v112, v18
	v_fmac_f32_e32 v115, v114, v28
	v_mul_f32_e32 v115, v108, v115
	v_mul_f32_e32 v116, 0xbfb8aa3b, v110
	v_exp_f32_e32 v116, v116
	s_nop 0
	v_add_f32_e32 v116, 1.0, v116
	v_div_scale_f32 v118, s[52:53], v116, v116, v110
	v_rcp_f32_e32 v119, v118
	s_nop 0
	v_fma_f32 v120, -v118, v119, 1.0
	v_fmac_f32_e32 v119, v120, v119
	v_div_scale_f32 v120, vcc, v110, v116, v110
	v_mul_f32_e32 v121, v120, v119
	v_fma_f32 v122, -v118, v121, v120
	v_fmac_f32_e32 v121, v122, v119
	v_fma_f32 v118, -v118, v121, v120
	v_div_fmas_f32 v118, v118, v119, v121
	v_div_fixup_f32 v117, v118, v116, v110
	v_mul_f32_e32 v124, v115, v117
	v_mul_f32_e32 v112, v97, v99
	v_mul_f32_e32 v113, v101, v103
	v_mul_f32_e32 v114, v105, v107
	v_mul_f32_e32 v115, v113, v11
	v_fmac_f32_e32 v115, v112, v19
	v_fmac_f32_e32 v115, v114, v29
	v_mul_f32_e32 v115, v109, v115
	v_mul_f32_e32 v116, 0xbfb8aa3b, v111
	v_exp_f32_e32 v116, v116
	s_nop 0
	v_add_f32_e32 v116, 1.0, v116
	v_div_scale_f32 v118, s[52:53], v116, v116, v111
	v_rcp_f32_e32 v119, v118
	s_nop 0
	v_fma_f32 v120, -v118, v119, 1.0
	v_fmac_f32_e32 v119, v120, v119
	v_div_scale_f32 v120, vcc, v111, v116, v111
	v_mul_f32_e32 v121, v120, v119
	v_fma_f32 v122, -v118, v121, v120
	v_fmac_f32_e32 v121, v122, v119
	v_fma_f32 v118, -v118, v121, v120
	v_div_fmas_f32 v118, v118, v119, v121
	v_div_fixup_f32 v117, v118, v116, v111
	v_mul_f32_e32 v125, v115, v117
	v_cvt_pk_bf16_f32 v131, v124, v125
	s_cmp_lt_u32 s55, 0x18000
	s_cbranch_scc0 .Lcv_nsB652
	global_store_dwordx4 v2, v[128:131], s[10:11]
.Lcv_nsB652:
	s_cmp_ge_u32 s54, 0x18000
	s_cbranch_scc1 .Lcv_done
	s_mov_b32 s55, s0
	s_min_u32 s51, s0, 0x17fff
	s_cmp_lt_u32 s51, 0x10000
	s_movk_i32 s1, 0xfff
	s_cselect_b32 s1, 0x1fff, s1
	s_and_b32 s5, s51, s1
	s_mul_i32 s10, s51, 0x1e00
	s_add_u32 s10, s10, s48
	s_addc_u32 s11, s49, 0
	s_cmp_lg_u32 s5, 0
	s_cselect_b64 s[44:45], -1, 0
	s_cselect_b32 s4, 0x1e00, 0
	s_cmp_lg_u32 s5, s1
	s_cselect_b64 s[46:47], -1, 0
	s_cselect_b32 s8, 0x1e00, 0
	s_sub_u32 s4, s10, s4
	s_subb_u32 s5, s11, 0
	s_add_u32 s8, s10, s8
	s_addc_u32 s9, s11, 0
	global_load_dwordx4 v[64:67], v2, s[10:11] offset:1024
	global_load_dwordx4 v[68:71], v2, s[10:11] offset:2048
	global_load_dwordx4 v[72:75], v2, s[10:11]
	global_load_dwordx4 v[76:79], v25, s[10:11] offset:1024
	global_load_dwordx4 v[80:83], v2, s[4:5] offset:1024
	global_load_dwordx4 v[84:87], v2, s[4:5] offset:2048
	global_load_dwordx4 v[88:91], v2, s[8:9] offset:1024
	global_load_dwordx4 v[92:95], v2, s[8:9] offset:2048
	s_add_i32 s0, s0, s50
	s_waitcnt vmcnt(9)
	s_branch .Lcv_loop2
; DI float bflo(unsigned w) { return __uint_as_float(w << 16); }
; DI float bfhi(unsigned w) { return __uint_as_float(w & 0xffff0000u); }
; DI float silu(float z) { return z / (1.f + __expf(-z)); }
; DI void phase_mix_even(char* lds, const Params& p, int layer, int dry) {
;     ...
;     { const u32x4 a = *(const u32x4*)(ur + 512 + c0), b = *(const u32x4*)(ur + 1024 + c0);
; #pragma unroll
;       for (int j = 0; j < 4; ++j) { ic[2 * j] = bflo(a[j]) * bflo(b[j]); ic[2 * j + 1] = bfhi(a[j]) * bfhi(b[j]); } }
;     if (pos > 0) { const u32x4 a = *(const u32x4*)(ur - UW + 512 + c0), b = *(const u32x4*)(ur - UW + 1024 + c0);
; #pragma unroll
;       for (int j = 0; j < 4; ++j) { il[2 * j] = bflo(a[j]) * bflo(b[j]); il[2 * j + 1] = bfhi(a[j]) * bfhi(b[j]); } }
;     else {
; #pragma unroll
;       for (int j = 0; j < 8; ++j) il[j] = 0.f; }
;     if (pos < S - 1) { const u32x4 a = *(const u32x4*)(ur + UW + 512 + c0), b = *(const u32x4*)(ur + UW + 1024 + c0);
; #pragma unroll
;       for (int j = 0; j < 4; ++j) { ir[2 * j] = bflo(a[j]) * bflo(b[j]); ir[2 * j + 1] = bfhi(a[j]) * bfhi(b[j]); } }
;     else {
; #pragma unroll
;       for (int j = 0; j < 8; ++j) ir[j] = 0.f; }
;     const u32x4 gbw = *(const u32x4*)(ur + c0), zw = *(const u32x4*)(ur + 2560 + c0);
;     float y[8];
; #pragma unroll
;     for (int j = 0; j < 8; ++j) {
;       const float gb = (j & 1) ? bfhi(gbw[j >> 1]) : bflo(gbw[j >> 1]);
;       const float z = (j & 1) ? bfhi(zw[j >> 1]) : bflo(zw[j >> 1]);
;       const float cv = il[j] * cw[c0 + j] + ic[j] * cw[512 + c0 + j] + ir[j] * cw[1024 + c0 + j];
;       y[j] = gb * cv * silu(z);
.Lcv_loop2:
	v_cndmask_b32_e64 v48, 0, v48, s[40:41]
	v_cndmask_b32_e64 v56, 0, v56, s[42:43]
	v_cndmask_b32_e64 v49, 0, v49, s[40:41]
	v_cndmask_b32_e64 v57, 0, v57, s[42:43]
	v_cndmask_b32_e64 v50, 0, v50, s[40:41]
	v_cndmask_b32_e64 v58, 0, v58, s[42:43]
	v_cndmask_b32_e64 v51, 0, v51, s[40:41]
	v_cndmask_b32_e64 v59, 0, v59, s[42:43]
	v_lshlrev_b32_e32 v96, 16, v32
	v_and_b32_e32 v97, 0xffff0000, v32
	v_lshlrev_b32_e32 v98, 16, v36
	v_and_b32_e32 v99, 0xffff0000, v36
	v_lshlrev_b32_e32 v100, 16, v48
	v_and_b32_e32 v101, 0xffff0000, v48
	v_lshlrev_b32_e32 v102, 16, v52
	v_and_b32_e32 v103, 0xffff0000, v52
	v_lshlrev_b32_e32 v104, 16, v56
	v_and_b32_e32 v105, 0xffff0000, v56
	v_lshlrev_b32_e32 v106, 16, v60
	v_and_b32_e32 v107, 0xffff0000, v60
	v_lshlrev_b32_e32 v108, 16, v40
	v_and_b32_e32 v109, 0xffff0000, v40
	v_lshlrev_b32_e32 v110, 16, v44
	v_and_b32_e32 v111, 0xffff0000, v44
	v_mul_f32_e32 v112, v96, v98
	v_mul_f32_e32 v113, v100, v102
	v_mul_f32_e32 v114, v104, v106
	v_mul_f32_e32 v115, v113, v4
	v_fmac_f32_e32 v115, v112, v12
	v_fmac_f32_e32 v115, v114, v20
	v_mul_f32_e32 v115, v108, v115
	v_mul_f32_e32 v116, 0xbfb8aa3b, v110
	v_exp_f32_e32 v116, v116
	s_nop 0
	v_add_f32_e32 v116, 1.0, v116
	v_div_scale_f32 v118, s[52:53], v116, v116, v110
	v_rcp_f32_e32 v119, v118
	s_nop 0
	v_fma_f32 v120, -v118, v119, 1.0
	v_fmac_f32_e32 v119, v120, v119
	v_div_scale_f32 v120, vcc, v110, v116, v110
	v_mul_f32_e32 v121, v120, v119
	v_fma_f32 v122, -v118, v121, v120
	v_fmac_f32_e32 v121, v122, v119
	v_fma_f32 v118, -v118, v121, v120
	v_div_fmas_f32 v118, v118, v119, v121
	v_div_fixup_f32 v117, v118, v116, v110
	v_mul_f32_e32 v124, v115, v117
	v_mul_f32_e32 v112, v97, v99
	v_mul_f32_e32 v113, v101, v103
	v_mul_f32_e32 v114, v105, v107
	v_mul_f32_e32 v115, v113, v5
	v_fmac_f32_e32 v115, v112, v13
	v_fmac_f32_e32 v115, v114, v21
	v_mul_f32_e32 v115, v109, v115
	v_mul_f32_e32 v116, 0xbfb8aa3b, v111
	v_exp_f32_e32 v116, v116
	s_nop 0
	v_add_f32_e32 v116, 1.0, v116
	v_div_scale_f32 v118, s[52:53], v116, v116, v111
	v_rcp_f32_e32 v119, v118
	s_nop 0
	v_fma_f32 v120, -v118, v119, 1.0
	v_fmac_f32_e32 v119, v120, v119
	v_div_scale_f32 v120, vcc, v111, v116, v111
	v_mul_f32_e32 v121, v120, v119
	v_fma_f32 v122, -v118, v121, v120
	v_fmac_f32_e32 v121, v122, v119
	v_fma_f32 v118, -v118, v121, v120
	v_div_fmas_f32 v118, v118, v119, v121
	v_div_fixup_f32 v117, v118, v116, v111
	v_mul_f32_e32 v125, v115, v117
	v_cvt_pk_bf16_f32 v128, v124, v125
	v_lshlrev_b32_e32 v96, 16, v33
	v_and_b32_e32 v97, 0xffff0000, v33
	v_lshlrev_b32_e32 v98, 16, v37
	v_and_b32_e32 v99, 0xffff0000, v37
	v_lshlrev_b32_e32 v100, 16, v49
	v_and_b32_e32 v101, 0xffff0000, v49
	v_lshlrev_b32_e32 v102, 16, v53
	v_and_b32_e32 v103, 0xffff0000, v53
	v_lshlrev_b32_e32 v104, 16, v57
	v_and_b32_e32 v105, 0xffff0000, v57
	v_lshlrev_b32_e32 v106, 16, v61
	v_and_b32_e32 v107, 0xffff0000, v61
	v_lshlrev_b32_e32 v108, 16, v41
	v_and_b32_e32 v109, 0xffff0000, v41
	v_lshlrev_b32_e32 v110, 16, v45
	v_and_b32_e32 v111, 0xffff0000, v45
	v_mul_f32_e32 v112, v96, v98
	v_mul_f32_e32 v113, v100, v102
	v_mul_f32_e32 v114, v104, v106
	v_mul_f32_e32 v115, v113, v6
	v_fmac_f32_e32 v115, v112, v14
	v_fmac_f32_e32 v115, v114, v22
	v_mul_f32_e32 v115, v108, v115
	v_mul_f32_e32 v116, 0xbfb8aa3b, v110
	v_exp_f32_e32 v116, v116
	s_nop 0
	v_add_f32_e32 v116, 1.0, v116
	v_div_scale_f32 v118, s[52:53], v116, v116, v110
	v_rcp_f32_e32 v119, v118
	s_nop 0
	v_fma_f32 v120, -v118, v119, 1.0
	v_fmac_f32_e32 v119, v120, v119
	v_div_scale_f32 v120, vcc, v110, v116, v110
	v_mul_f32_e32 v121, v120, v119
	v_fma_f32 v122, -v118, v121, v120
	v_fmac_f32_e32 v121, v122, v119
	v_fma_f32 v118, -v118, v121, v120
	v_div_fmas_f32 v118, v118, v119, v121
	v_div_fixup_f32 v117, v118, v116, v110
	v_mul_f32_e32 v124, v115, v117
	v_mul_f32_e32 v112, v97, v99
	v_mul_f32_e32 v113, v101, v103
	v_mul_f32_e32 v114, v105, v107
	v_mul_f32_e32 v115, v113, v7
	v_fmac_f32_e32 v115, v112, v15
	v_fmac_f32_e32 v115, v114, v23
	v_mul_f32_e32 v115, v109, v115
	v_mul_f32_e32 v116, 0xbfb8aa3b, v111
	v_exp_f32_e32 v116, v116
	s_nop 0
	v_add_f32_e32 v116, 1.0, v116
	v_div_scale_f32 v118, s[52:53], v116, v116, v111
	v_rcp_f32_e32 v119, v118
	s_nop 0
	v_fma_f32 v120, -v118, v119, 1.0
	v_fmac_f32_e32 v119, v120, v119
	v_div_scale_f32 v120, vcc, v111, v116, v111
	v_mul_f32_e32 v121, v120, v119
	v_fma_f32 v122, -v118, v121, v120
	v_fmac_f32_e32 v121, v122, v119
	v_fma_f32 v118, -v118, v121, v120
	v_div_fmas_f32 v118, v118, v119, v121
; DI unsigned cvtpk(float lo, float hi) { f32x2 v = {lo, hi}; bf16x2_t b = __builtin_convertvector(v, bf16x2_t); return __builtin_bit_cast(unsigned, b); }
; DI float bflo(unsigned w) { return __uint_as_float(w << 16); }
; DI float bfhi(unsigned w) { return __uint_as_float(w & 0xffff0000u); }
; DI float silu(float z) { return z / (1.f + __expf(-z)); }
; DI void phase_mix_even(char* lds, const Params& p, int layer, int dry) {
;     ...
;     const u32x4 gbw = *(const u32x4*)(ur + c0), zw = *(const u32x4*)(ur + 2560 + c0);
;     float y[8];
; #pragma unroll
;     for (int j = 0; j < 8; ++j) {
;       const float gb = (j & 1) ? bfhi(gbw[j >> 1]) : bflo(gbw[j >> 1]);
;       const float z = (j & 1) ? bfhi(zw[j >> 1]) : bflo(zw[j >> 1]);
;       const float cv = il[j] * cw[c0 + j] + ic[j] * cw[512 + c0 + j] + ir[j] * cw[1024 + c0 + j];
;       y[j] = gb * cv * silu(z);
;     }
;     u32x4 w; w.x = cvtpk(y[0], y[1]); w.y = cvtpk(y[2], y[3]); w.z = cvtpk(y[4], y[5]); w.w = cvtpk(y[6], y[7]);
;     if (!dry) *(u32x4*)(ur + c0) = w;
	v_div_fixup_f32 v117, v118, v116, v111
	v_mul_f32_e32 v125, v115, v117
	v_cvt_pk_bf16_f32 v129, v124, v125
	v_lshlrev_b32_e32 v96, 16, v34
	v_and_b32_e32 v97, 0xffff0000, v34
	v_lshlrev_b32_e32 v98, 16, v38
	v_and_b32_e32 v99, 0xffff0000, v38
	v_lshlrev_b32_e32 v100, 16, v50
	v_and_b32_e32 v101, 0xffff0000, v50
	v_lshlrev_b32_e32 v102, 16, v54
	v_and_b32_e32 v103, 0xffff0000, v54
	v_lshlrev_b32_e32 v104, 16, v58
	v_and_b32_e32 v105, 0xffff0000, v58
	v_lshlrev_b32_e32 v106, 16, v62
	v_and_b32_e32 v107, 0xffff0000, v62
	v_lshlrev_b32_e32 v108, 16, v42
	v_and_b32_e32 v109, 0xffff0000, v42
	v_lshlrev_b32_e32 v110, 16, v46
	v_and_b32_e32 v111, 0xffff0000, v46
	v_mul_f32_e32 v112, v96, v98
	v_mul_f32_e32 v113, v100, v102
	v_mul_f32_e32 v114, v104, v106
	v_mul_f32_e32 v115, v113, v8
	v_fmac_f32_e32 v115, v112, v16
	v_fmac_f32_e32 v115, v114, v26
	v_mul_f32_e32 v115, v108, v115
	v_mul_f32_e32 v116, 0xbfb8aa3b, v110
	v_exp_f32_e32 v116, v116
	s_nop 0
	v_add_f32_e32 v116, 1.0, v116
	v_div_scale_f32 v118, s[52:53], v116, v116, v110
	v_rcp_f32_e32 v119, v118
	s_nop 0
	v_fma_f32 v120, -v118, v119, 1.0
	v_fmac_f32_e32 v119, v120, v119
	v_div_scale_f32 v120, vcc, v110, v116, v110
	v_mul_f32_e32 v121, v120, v119
	v_fma_f32 v122, -v118, v121, v120
	v_fmac_f32_e32 v121, v122, v119
	v_fma_f32 v118, -v118, v121, v120
	v_div_fmas_f32 v118, v118, v119, v121
	v_div_fixup_f32 v117, v118, v116, v110
	v_mul_f32_e32 v124, v115, v117
	v_mul_f32_e32 v112, v97, v99
	v_mul_f32_e32 v113, v101, v103
	v_mul_f32_e32 v114, v105, v107
	v_mul_f32_e32 v115, v113, v9
	v_fmac_f32_e32 v115, v112, v17
	v_fmac_f32_e32 v115, v114, v27
	v_mul_f32_e32 v115, v109, v115
	v_mul_f32_e32 v116, 0xbfb8aa3b, v111
	v_exp_f32_e32 v116, v116
	s_nop 0
	v_add_f32_e32 v116, 1.0, v116
	v_div_scale_f32 v118, s[52:53], v116, v116, v111
	v_rcp_f32_e32 v119, v118
	s_nop 0
	v_fma_f32 v120, -v118, v119, 1.0
	v_fmac_f32_e32 v119, v120, v119
	v_div_scale_f32 v120, vcc, v111, v116, v111
	v_mul_f32_e32 v121, v120, v119
	v_fma_f32 v122, -v118, v121, v120
	v_fmac_f32_e32 v121, v122, v119
	v_fma_f32 v118, -v118, v121, v120
	v_div_fmas_f32 v118, v118, v119, v121
	v_div_fixup_f32 v117, v118, v116, v111
	v_mul_f32_e32 v125, v115, v117
	v_cvt_pk_bf16_f32 v130, v124, v125
	v_lshlrev_b32_e32 v96, 16, v35
	v_and_b32_e32 v97, 0xffff0000, v35
	v_lshlrev_b32_e32 v98, 16, v39
	v_and_b32_e32 v99, 0xffff0000, v39
	v_lshlrev_b32_e32 v100, 16, v51
	v_and_b32_e32 v101, 0xffff0000, v51
	v_lshlrev_b32_e32 v102, 16, v55
	v_and_b32_e32 v103, 0xffff0000, v55
	v_lshlrev_b32_e32 v104, 16, v59
	v_and_b32_e32 v105, 0xffff0000, v59
	v_lshlrev_b32_e32 v106, 16, v63
	v_and_b32_e32 v107, 0xffff0000, v63
	v_lshlrev_b32_e32 v108, 16, v43
	v_and_b32_e32 v109, 0xffff0000, v43
	v_lshlrev_b32_e32 v110, 16, v47
	v_and_b32_e32 v111, 0xffff0000, v47
	v_mul_f32_e32 v112, v96, v98
	v_mul_f32_e32 v113, v100, v102
	v_mul_f32_e32 v114, v104, v106
	v_mul_f32_e32 v115, v113, v10
	v_fmac_f32_e32 v115, v112, v18
	v_fmac_f32_e32 v115, v114, v28
	v_mul_f32_e32 v115, v108, v115
	v_mul_f32_e32 v116, 0xbfb8aa3b, v110
	v_exp_f32_e32 v116, v116
	s_nop 0
	v_add_f32_e32 v116, 1.0, v116
	v_div_scale_f32 v118, s[52:53], v116, v116, v110
	v_rcp_f32_e32 v119, v118
	s_nop 0
	v_fma_f32 v120, -v118, v119, 1.0
	v_fmac_f32_e32 v119, v120, v119
	v_div_scale_f32 v120, vcc, v110, v116, v110
	v_mul_f32_e32 v121, v120, v119
	v_fma_f32 v122, -v118, v121, v120
	v_fmac_f32_e32 v121, v122, v119
	v_fma_f32 v118, -v118, v121, v120
	v_div_fmas_f32 v118, v118, v119, v121
	v_div_fixup_f32 v117, v118, v116, v110
	v_mul_f32_e32 v124, v115, v117
	v_mul_f32_e32 v112, v97, v99
	v_mul_f32_e32 v113, v101, v103
	v_mul_f32_e32 v114, v105, v107
	v_mul_f32_e32 v115, v113, v11
	v_fmac_f32_e32 v115, v112, v19
	v_fmac_f32_e32 v115, v114, v29
	v_mul_f32_e32 v115, v109, v115
	v_mul_f32_e32 v116, 0xbfb8aa3b, v111
	v_exp_f32_e32 v116, v116
	s_nop 0
	v_add_f32_e32 v116, 1.0, v116
	v_div_scale_f32 v118, s[52:53], v116, v116, v111
	v_rcp_f32_e32 v119, v118
	s_nop 0
	v_fma_f32 v120, -v118, v119, 1.0
	v_fmac_f32_e32 v119, v120, v119
	v_div_scale_f32 v120, vcc, v111, v116, v111
	v_mul_f32_e32 v121, v120, v119
	v_fma_f32 v122, -v118, v121, v120
	v_fmac_f32_e32 v121, v122, v119
	v_fma_f32 v118, -v118, v121, v120
	v_div_fmas_f32 v118, v118, v119, v121
	v_div_fixup_f32 v117, v118, v116, v111
	v_mul_f32_e32 v125, v115, v117
	v_cvt_pk_bf16_f32 v131, v124, v125
	s_cmp_lt_u32 s54, 0x18000
	s_cbranch_scc0 .Lcv_nsA957
	global_store_dwordx4 v2, v[128:131], s[2:3]

; DI unsigned cvtpk(float lo, float hi) { f32x2 v = {lo, hi}; bf16x2_t b = __builtin_convertvector(v, bf16x2_t); return __builtin_bit_cast(unsigned, b); }
; DI float bflo(unsigned w) { return __uint_as_float(w << 16); }
; DI float bfhi(unsigned w) { return __uint_as_float(w & 0xffff0000u); }
; DI int ltid() { int t; asm volatile("v_mov_b32 %0, %1" : "=v"(t) : "v"(threadIdx.x)); return t; }
; DI float silu(float z) { return z / (1.f + __expf(-z)); }
; DI void phase_mix_even(char* lds, const Params& p, int layer, int dry) {
;     ...
;   const float* cw = p.conv_w + e * 3 * 512;
;   for (int idx = blockIdx.x * NTHREADS + ltid(); idx < NTOK * 64; idx += gridDim.x * NTHREADS) {
;     const int t = idx >> 6, c0 = (idx & 63) * 8;
;     int S, seq0, pos, sq; tok_info(t, S, seq0, pos, sq);
;     bf16_t* ur = p.u + (size_t)t * UW;
;     float ic[8], il[8], ir[8];
;     { const u32x4 a = *(const u32x4*)(ur + 512 + c0), b = *(const u32x4*)(ur + 1024 + c0);
; #pragma unroll
;       for (int j = 0; j < 4; ++j) { ic[2 * j] = bflo(a[j]) * bflo(b[j]); ic[2 * j + 1] = bfhi(a[j]) * bfhi(b[j]); } }
;     if (pos > 0) { const u32x4 a = *(const u32x4*)(ur - UW + 512 + c0), b = *(const u32x4*)(ur - UW + 1024 + c0);
; #pragma unroll
;       for (int j = 0; j < 4; ++j) { il[2 * j] = bflo(a[j]) * bflo(b[j]); il[2 * j + 1] = bfhi(a[j]) * bfhi(b[j]); } }
;     else {
; #pragma unroll
;       for (int j = 0; j < 8; ++j) il[j] = 0.f; }
;     if (pos < S - 1) { const u32x4 a = *(const u32x4*)(ur + UW + 512 + c0), b = *(const u32x4*)(ur + UW + 1024 + c0);
; #pragma unroll
;       for (int j = 0; j < 4; ++j) { ir[2 * j] = bflo(a[j]) * bflo(b[j]); ir[2 * j + 1] = bfhi(a[j]) * bfhi(b[j]); } }
;     else {
; #pragma unroll
;       for (int j = 0; j < 8; ++j) ir[j] = 0.f; }
;     const u32x4 gbw = *(const u32x4*)(ur + c0), zw = *(const u32x4*)(ur + 2560 + c0);
;     float y[8];
; #pragma unroll
;     for (int j = 0; j < 8; ++j) {
;       const float gb = (j & 1) ? bfhi(gbw[j >> 1]) : bflo(gbw[j >> 1]);
;       const float z = (j & 1) ? bfhi(zw[j >> 1]) : bflo(zw[j >> 1]);
;       const float cv = il[j] * cw[c0 + j] + ic[j] * cw[512 + c0 + j] + ir[j] * cw[1024 + c0 + j];
;       y[j] = gb * cv * silu(z);
;     }
;     u32x4 w; w.x = cvtpk(y[0], y[1]); w.y = cvtpk(y[2], y[3]); w.z = cvtpk(y[4], y[5]); w.w = cvtpk(y[6], y[7]);
;     if (!dry) *(u32x4*)(ur + c0) = w;
;   }
.Lcv_done:
	s_waitcnt vmcnt(0)
	v_readlane_b32 s40, v254, 33
	v_readlane_b32 s41, v254, 34
	v_readlane_b32 s42, v254, 35
	v_readlane_b32 s43, v254, 36
	v_readlane_b32 s44, v254, 37
	v_readlane_b32 s45, v254, 38
	v_readlane_b32 s46, v254, 39
	v_readlane_b32 s47, v254, 40
	v_readlane_b32 s48, v254, 41
	v_readlane_b32 s49, v254, 42
	v_readlane_b32 s50, v254, 43
	v_readlane_b32 s51, v254, 44
	v_readlane_b32 s52, v254, 45
	v_readlane_b32 s53, v254, 46
	v_readlane_b32 s54, v254, 47
	v_readlane_b32 s55, v254, 48
	s_mov_b64 s[0:1], exec
	s_branch .LBB0_215
